# fox_prep V^T store loop: 16 ds_read_u16 per iteration issued together; 64-lane sum butterflies in the two rmsnorm phases and the SSD group-norm phase done with DPP row ops + v_permlane16/32_swap inste
# speedup vs baseline: 1.0166x; 1.0071x over previous
; __device__ __forceinline__ int rstd_slot(int row) { const int rr = row & 255; return (row & ~255) + ((((rr >> 6) & 1) * 16 + (rr & 15)) * 8 + (rr >> 7) * 4 + ((rr >> 4) & 3)); }
; __device__ __forceinline__ float wave_sum(float v) {
; #pragma unroll
;     for (int o = 1; o < 64; o <<= 1) v += __shfl_xor(v, o);
;     return v;
; }
; template <bool BIN, bool WRITE_U> __device__ __forceinline__ void norm_phase(const void* hin_, const float* gain, bf16* U, const float* Wg, int ldw, int goff, int ng, float* GATE, float* RSTD, unsigned char* lds) {
;     ...
;     for (int row = gw; row < M_; row += NGW) {
;         f32x4 v[4]; float ss = 0.f;
; #pragma unroll
;         for (int j = 0; j < 4; ++j) { v[j] = nxt[j]; nxt[j] = nx2[j]; ss += (v[j].x * v[j].x + v[j].y * v[j].y) + (v[j].z * v[j].z + v[j].w * v[j].w); }
;         if (row + 2 * NGW < M_) NP_LOADROW(nx2, row + 2 * NGW);
;         const float rstd = rsqrtf(wave_sum(ss) * (1.f / D_) + EPS_);
;         if (lane == 0) RSTD[rstd_slot(row)] = rstd;
.LBB0_196:
	s_or_b64 exec, exec, s[24:25]
	v_mul_f32_e32 v180, v159, v159
	v_mul_f32_e32 v181, v161, v161
	v_fmac_f32_e32 v180, v158, v158
	v_fmac_f32_e32 v181, v160, v160
	v_add_f32_e32 v180, v180, v181
	v_mul_f32_e32 v181, v51, v51
	v_mul_f32_e32 v182, v53, v53
	v_fmac_f32_e32 v181, v50, v50
	v_fmac_f32_e32 v182, v52, v52
	v_add_f32_e32 v181, v181, v182
	v_add_f32_e32 v180, v180, v181
	v_mul_f32_e32 v181, v23, v23
	v_mul_f32_e32 v182, v25, v25
	v_fmac_f32_e32 v181, v22, v22
	v_fmac_f32_e32 v182, v24, v24
	v_add_f32_e32 v181, v181, v182
	v_add_f32_e32 v180, v180, v181
	v_mul_f32_e32 v181, v3, v3
	v_mul_f32_e32 v182, v5, v5
	v_fmac_f32_e32 v181, v2, v2
	v_fmac_f32_e32 v182, v4, v4
	v_add_f32_e32 v181, v181, v182
	v_add_f32_e32 v180, v180, v181
	s_nop 1
	v_add_f32_dpp v180, v180, v180 quad_perm:[1,0,3,2] row_mask:0xf bank_mask:0xf
	s_nop 1
	v_add_f32_dpp v180, v180, v180 quad_perm:[2,3,0,1] row_mask:0xf bank_mask:0xf
	s_nop 1
	v_add_f32_dpp v180, v180, v180 row_half_mirror row_mask:0xf bank_mask:0xf
	s_nop 1
	v_add_f32_dpp v180, v180, v180 row_mirror row_mask:0xf bank_mask:0xf
	v_mov_b32_e32 v181, v180
	s_nop 1
	v_permlane16_swap_b32 v181, v180
	v_add_f32_e32 v180, v180, v181
	v_mov_b32_e32 v181, v180
	s_nop 1
	v_permlane32_swap_b32 v181, v180
	v_add_f32_e32 v180, v180, v181
	s_waitcnt lgkmcnt(0)
	v_fmamk_f32 v180, v180, 0x3a800000, v225
	v_mul_f32_e32 v181, 0x4b800000, v180
	v_cmp_gt_f32_e64 s[12:13], s91, v180
	s_nop 1
	v_cndmask_b32_e64 v180, v180, v181, s[12:13]
	v_rsq_f32_e32 v180, v180
	s_nop 0
	v_mul_f32_e32 v181, 0x45800000, v180
	v_cndmask_b32_e64 v193, v180, v181, s[12:13]
	s_and_saveexec_b64 s[12:13], vcc
	s_cbranch_execz .LBB0_198
	v_lshrrev_b32_e32 v181, 2, v186
	v_and_b32_e32 v182, 15, v186
	v_and_or_b32 v181, v181, 16, v182
	v_lshrrev_b32_e32 v182, 5, v186
	v_and_b32_e32 v182, 4, v182
	v_and_b32_e32 v180, 0xffffff00, v186
	v_lshl_or_b32 v181, v181, 3, v182
	v_bfe_u32 v182, v186, 4, 2
	v_or3_b32 v180, v181, v182, v180
	v_ashrrev_i32_e32 v181, 31, v180
	v_lshl_add_u64 v[180:181], v[180:181], 2, s[20:21]
	global_store_dword v[180:181], v193, off

; __device__ __forceinline__ int rstd_slot(int row) { const int rr = row & 255; return (row & ~255) + ((((rr >> 6) & 1) * 16 + (rr & 15)) * 8 + (rr >> 7) * 4 + ((rr >> 4) & 3)); }
; __device__ __forceinline__ float wave_sum(float v) {
; #pragma unroll
;     for (int o = 1; o < 64; o <<= 1) v += __shfl_xor(v, o);
;     return v;
; }
; template <bool BIN, bool WRITE_U> __device__ __forceinline__ void norm_phase(const void* hin_, const float* gain, bf16* U, const float* Wg, int ldw, int goff, int ng, float* GATE, float* RSTD, unsigned char* lds) {
;     ...
;     for (int row = gw; row < M_; row += NGW) {
;         f32x4 v[4]; float ss = 0.f;
; #pragma unroll
;         for (int j = 0; j < 4; ++j) { v[j] = nxt[j]; nxt[j] = nx2[j]; ss += (v[j].x * v[j].x + v[j].y * v[j].y) + (v[j].z * v[j].z + v[j].w * v[j].w); }
;         if (row + 2 * NGW < M_) NP_LOADROW(nx2, row + 2 * NGW);
;         const float rstd = rsqrtf(wave_sum(ss) * (1.f / D_) + EPS_);
;         if (lane == 0) RSTD[rstd_slot(row)] = rstd;
.LBB0_216:
	s_or_b64 exec, exec, s[20:21]
	v_mul_f32_e32 v180, v175, v175
	v_mul_f32_e32 v181, v177, v177
	v_fmac_f32_e32 v180, v174, v174
	v_fmac_f32_e32 v181, v176, v176
	v_add_f32_e32 v180, v180, v181
	v_mul_f32_e32 v181, v171, v171
	v_mul_f32_e32 v182, v173, v173
	v_fmac_f32_e32 v181, v170, v170
	v_fmac_f32_e32 v182, v172, v172
	v_add_f32_e32 v181, v181, v182
	v_add_f32_e32 v180, v180, v181
	v_mul_f32_e32 v181, v167, v167
	v_mul_f32_e32 v182, v169, v169
	v_fmac_f32_e32 v181, v166, v166
	v_fmac_f32_e32 v182, v168, v168
	v_add_f32_e32 v181, v181, v182
	v_add_f32_e32 v180, v180, v181
	v_mul_f32_e32 v181, v163, v163
	v_mul_f32_e32 v182, v165, v165
	v_fmac_f32_e32 v181, v162, v162
	v_fmac_f32_e32 v182, v164, v164
	v_add_f32_e32 v181, v181, v182
	v_add_f32_e32 v180, v180, v181
	s_nop 1
	v_add_f32_dpp v180, v180, v180 quad_perm:[1,0,3,2] row_mask:0xf bank_mask:0xf
	s_nop 1
	v_add_f32_dpp v180, v180, v180 quad_perm:[2,3,0,1] row_mask:0xf bank_mask:0xf
	s_nop 1
	v_add_f32_dpp v180, v180, v180 row_half_mirror row_mask:0xf bank_mask:0xf
	s_nop 1
	v_add_f32_dpp v180, v180, v180 row_mirror row_mask:0xf bank_mask:0xf
	v_mov_b32_e32 v181, v180
	s_nop 1
	v_permlane16_swap_b32 v181, v180
	v_add_f32_e32 v180, v180, v181
	v_mov_b32_e32 v181, v180
	s_nop 1
	v_permlane32_swap_b32 v181, v180
	v_add_f32_e32 v180, v180, v181
	s_waitcnt lgkmcnt(0)
	v_fmamk_f32 v180, v180, 0x3a800000, v225
	v_mul_f32_e32 v181, 0x4b800000, v180
	v_cmp_gt_f32_e64 s[12:13], s91, v180
	s_nop 1
	v_cndmask_b32_e64 v180, v180, v181, s[12:13]
	v_rsq_f32_e32 v180, v180
	s_nop 0
	v_mul_f32_e32 v181, 0x45800000, v180
	v_cndmask_b32_e64 v195, v180, v181, s[12:13]
	s_and_saveexec_b64 s[12:13], vcc
	s_cbranch_execz .LBB0_218
	v_lshrrev_b32_e32 v181, 2, v186
	v_and_b32_e32 v182, 15, v186
	v_and_or_b32 v181, v181, 16, v182
	v_lshrrev_b32_e32 v182, 5, v186
	v_and_b32_e32 v182, 4, v182
	v_and_b32_e32 v180, 0xffffff00, v186
	v_lshl_or_b32 v181, v181, 3, v182
	v_bfe_u32 v182, v186, 4, 2
	v_or3_b32 v180, v181, v182, v180
	v_ashrrev_i32_e32 v181, 31, v180
	v_lshl_add_u64 v[180:181], v[180:181], 2, s[18:19]
	global_store_dword v[180:181], v195, off

; __device__ __forceinline__ unsigned pk2(float lo, float hi) { f32x2_t v = {lo, hi}; bf16x2_hw b = __builtin_convertvector(v, bf16x2_hw); return __builtin_bit_cast(unsigned, b); }
; __device__ __forceinline__ float bflo(unsigned u) { return __uint_as_float(u << 16); }
; __device__ __forceinline__ float bfhi(unsigned u) { return __uint_as_float(u & 0xffff0000u); }
; __device__ __forceinline__ float wave_sum(float v) {
; #pragma unroll
;     for (int o = 1; o < 64; o <<= 1) v += __shfl_xor(v, o);
;     return v;
; }
; __device__ __forceinline__ void ssd_norm_phase(ArgsP a, int j) {
;     ...
; #pragma unroll 4
;     for (int it = gw; it < M_ * 2; it += NGW) { const int tok = it >> 1, grp = it & 1;
;         const u32x2 t2 = *(const u32x2*)(TMP + (size_t)tok * 512 + grp * 256 + lane * 4);
;         const f32x4 v = (f32x4){bflo(t2.x), bfhi(t2.x), bflo(t2.y), bfhi(t2.y)};
;         const float rs = rsqrtf(wave_sum((v.x * v.x + v.y * v.y) + (v.z * v.z + v.w * v.w)) * (1.f / 256.f) + EPS_);
;         const f32x4 w = *(const f32x4*)(nw + grp * 256 + lane * 4);
;         u32x2 o; o.x = pk2(v.x * rs * w.x, v.y * rs * w.y); o.y = pk2(v.z * rs * w.z, v.w * rs * w.w);
;         *(u32x2*)(Y + (size_t)tok * D_ + 512 + grp * 256 + lane * 4) = o; }
.LBB0_778:
	v_ashrrev_i32_e32 v18, 1, v1
	v_ashrrev_i32_e32 v19, 31, v18
	v_and_b32_e32 v13, 0x100, v12
	v_lshlrev_b64 v[14:15], 10, v[18:19]
	v_mov_b32_e32 v21, v0
	v_lshlrev_b32_e32 v20, 1, v13
	v_lshl_add_u64 v[14:15], s[6:7], 0, v[14:15]
	v_mov_b32_e32 v5, v0
	v_lshl_add_u64 v[14:15], v[14:15], 0, v[20:21]
	v_lshl_add_u64 v[14:15], v[14:15], 0, v[4:5]
	global_load_dwordx2 v[22:23], v[14:15], off
	v_mov_b32_e32 v15, v0
	v_lshlrev_b32_e32 v14, 2, v13
	v_lshl_add_u64 v[14:15], v[2:3], 0, v[14:15]
	global_load_dwordx4 v[14:17], v[14:15], off
	v_lshlrev_b64 v[18:19], 11, v[18:19]
	v_lshl_add_u64 v[18:19], s[4:5], 0, v[18:19]
	v_lshl_add_u64 v[18:19], v[18:19], 0, v[20:21]
	v_lshl_add_u64 v[18:19], v[18:19], 0, v[4:5]
	v_add_u32_e32 v1, s10, v1
	v_cmp_lt_i32_e32 vcc, s77, v1
	s_or_b64 s[8:9], vcc, s[8:9]
	v_add_co_u32_e32 v18, vcc, 0x6800000, v18
	v_add_u32_e32 v12, s11, v12
	s_nop 0
	v_addc_co_u32_e32 v19, vcc, 0, v19, vcc
	s_waitcnt vmcnt(1)
	v_and_b32_e32 v21, 0xffff0000, v23
	v_and_b32_e32 v25, 0xffff0000, v22
	v_lshlrev_b32_e32 v20, 16, v23
	v_lshlrev_b32_e32 v24, 16, v22
	v_mov_b32_e32 v26, v25
	v_mov_b32_e32 v27, v21
	v_mov_b32_e32 v22, v24
	v_mov_b32_e32 v23, v20
	v_pk_mul_f32 v[26:27], v[26:27], v[26:27]
	s_nop 0
	v_pk_fma_f32 v[22:23], v[22:23], v[22:23], v[26:27]
	s_nop 0
	v_add_f32_e32 v5, v22, v23
	s_nop 1
	v_add_f32_dpp v5, v5, v5 quad_perm:[1,0,3,2] row_mask:0xf bank_mask:0xf
	s_nop 1
	v_add_f32_dpp v5, v5, v5 quad_perm:[2,3,0,1] row_mask:0xf bank_mask:0xf
	s_nop 1
	v_add_f32_dpp v5, v5, v5 row_half_mirror row_mask:0xf bank_mask:0xf
	s_nop 1
	v_add_f32_dpp v5, v5, v5 row_mirror row_mask:0xf bank_mask:0xf
	v_mov_b32_e32 v13, v5
	s_nop 1
	v_permlane16_swap_b32 v13, v5
	v_add_f32_e32 v5, v5, v13
	v_mov_b32_e32 v13, v5
	s_nop 1
	v_permlane32_swap_b32 v13, v5
	v_add_f32_e32 v5, v5, v13
	s_waitcnt lgkmcnt(0)
	v_fmamk_f32 v5, v5, 0x3b800000, v225
	v_mul_f32_e32 v13, 0x4b800000, v5
	v_cmp_gt_f32_e32 vcc, s91, v5
	s_nop 1
	v_cndmask_b32_e32 v5, v5, v13, vcc
	v_rsq_f32_e32 v5, v5
	s_nop 0
	v_mul_f32_e32 v13, 0x45800000, v5
	v_cndmask_b32_e32 v22, v5, v13, vcc
	v_pk_mul_f32 v[24:25], v[22:23], v[24:25] op_sel_hi:[0,1]
	v_pk_mul_f32 v[20:21], v[22:23], v[20:21] op_sel_hi:[0,1]
	s_waitcnt vmcnt(0)
	v_pk_mul_f32 v[14:15], v[14:15], v[24:25]
	v_pk_mul_f32 v[16:17], v[16:17], v[20:21]
	v_cvt_pk_bf16_f32 v14, v14, v15
	v_cvt_pk_bf16_f32 v15, v16, v17
	global_store_dwordx2 v[18:19], v[14:15], off offset:1024
	s_andn2_b64 exec, exec, s[8:9]
	s_cbranch_execnz .LBB0_778

; __device__ __forceinline__ void fox_prep(ArgsP a, int j, unsigned char* lds) {
;     ...
; #pragma unroll 2
;         for (int k = 0; k < 8; ++k) { const int id = tid + 512 * k, c8 = id & 7, d = (id >> 3) & 127, h = id >> 10;
;             const bf16* src = (const bf16*)(lds + (8 * c8) * 1028) + h * 128 + d;
;             u32x4 o;
; #pragma unroll
;             for (int e = 0; e < 4; ++e) { const int i0 = 2 * e, i1 = 2 * e + 1;
;                 const int r0 = 16 * (c8 >> 1) + 4 * (c8 & 1) + (i0 & 3) + 8 * (i0 >> 2) - 8 * c8, r1 = 16 * (c8 >> 1) + 4 * (c8 & 1) + (i1 & 3) + 8 * (i1 >> 2) - 8 * c8;
;                 o[e] = (unsigned)src[r0 * 514] | ((unsigned)src[r1 * 514] << 16); }
;             *(u32x4*)(VT + ((size_t)(b * 4 + h) * 128 + d) * T_ + tb * 64 + c8 * 8) = o; }
.LBB0_786:
	v_add_u32_e32 v31, s5, v1
	v_ashrrev_i32_e32 v34, 10, v31
	v_lshl_add_u32 v35, v34, 8, v44
	ds_read_u16 v112, v35
	ds_read_u16 v113, v35 offset:1028
	ds_read_u16 v114, v35 offset:2056
	ds_read_u16 v115, v35 offset:3084
	ds_read_u16 v116, v35 offset:8224
	ds_read_u16 v117, v35 offset:9252
	ds_read_u16 v118, v35 offset:10280
	ds_read_u16 v119, v35 offset:11308
	v_add_u32_e32 v34, s4, v34
	v_add_u32_e32 v31, 0x200, v31
	v_mov_b32_e32 v59, v0
	s_addk_i32 s5, 0x400
	v_bfe_u32 v53, v31, 3, 7
	v_ashrrev_i32_e32 v31, 10, v31
	v_lshl_add_u32 v76, v31, 8, v42
	v_lshlrev_b32_e32 v77, 1, v53
	v_add3_u32 v76, v76, v77, v43
	ds_read_u16 v120, v76
	ds_read_u16 v121, v76 offset:1028
	ds_read_u16 v122, v76 offset:2056
	ds_read_u16 v123, v76 offset:3084
	ds_read_u16 v124, v76 offset:8224
	ds_read_u16 v125, v76 offset:9252
	ds_read_u16 v126, v76 offset:10280
	ds_read_u16 v127, v76 offset:11308
	v_ashrrev_i32_e32 v35, 31, v34
	v_lshlrev_b64 v[34:35], 20, v[34:35]
	v_lshl_add_u64 v[34:35], v[32:33], 0, v[34:35]
	v_lshlrev_b32_e32 v58, 13, v53
	s_waitcnt lgkmcnt(8)
	v_lshl_or_b32 v54, v113, 16, v112
	v_lshl_or_b32 v55, v115, 16, v114
	v_lshl_or_b32 v56, v117, 16, v116
	v_lshl_or_b32 v57, v119, 16, v118
	global_store_dwordx4 v[34:35], v[54:57], off
	v_add_u32_e32 v34, s4, v31
	v_ashrrev_i32_e32 v35, 31, v34
	v_lshlrev_b64 v[34:35], 20, v[34:35]
	v_lshl_add_u64 v[34:35], s[0:1], 0, v[34:35]
	v_lshl_add_u64 v[34:35], v[34:35], 0, v[58:59]
	v_lshl_add_u64 v[34:35], v[34:35], 0, s[68:69]
	v_mov_b32_e32 v31, v0
	v_lshl_add_u64 v[34:35], v[34:35], 0, v[30:31]
	s_waitcnt lgkmcnt(0)
	v_lshl_or_b32 v60, v121, 16, v120
	v_lshl_or_b32 v61, v123, 16, v122
	v_lshl_or_b32 v62, v125, 16, v124
	v_lshl_or_b32 v63, v127, 16, v126
	global_store_dwordx4 v[34:35], v[60:63], off
	s_cmpk_eq_i32 s5, 0x1000
	s_cbranch_scc0 .LBB0_786
	s_mov_b32 s4, s72
	s_add_i32 s8, s4, s8
	s_cmpk_gt_i32 s8, 0x1ff
	s_cbranch_scc0 .LBB0_783
